# v22 + decode-first workgroups take 23 decode tasks, the other non-scan ones 20
# baseline (speedup 1.0000x reference)
.LBB0_1181:
.LBB0_1182:
	s_cmp_lt_i32 s52, 1
	s_cbranch_scc1 .LBB0_1187
	s_cmp_eq_u32 s52, 1
	s_cbranch_scc1 .LBB0_1185
	s_cmp_eq_u32 s52, 2
	s_cselect_b32 s52, 21, 41
	s_cbranch_execz .LBB0_1186
	s_branch .LBB0_1187

.LBB0_1188:
	s_and_b32 s6, s82, 3
	s_cmp_eq_u32 s6, 3
	s_cselect_b32 s7, 23, 20
	s_cmp_eq_u32 s6, 0
	s_cselect_b32 s6, 1, s7
	s_and_b64 s[4:5], s[4:5], exec
	s_cselect_b32 s44, s6, s25
	s_add_i32 s4, s83, -6
	s_cmp_lt_u32 s4, 2
	s_cselect_b64 s[4:5], -1, 0
	s_or_b64 s[20:21], s[4:5], s[0:1]
	s_add_u32 s45, s26, 0x29800000
	s_addc_u32 s46, s27, 0
	s_add_u32 s18, s26, 0x13200000
	v_readlane_b32 s0, v255, 23
	s_addc_u32 s19, s27, 0
	v_readlane_b32 s14, v255, 37
	v_readlane_b32 s15, v255, 38
	s_add_u32 s30, s14, 0x8200000
	s_addc_u32 s31, s15, 0
	s_add_u32 s47, s14, 0x8300000
	s_addc_u32 s48, s15, 0
	s_add_u32 s49, s26, 0x33a00000
	s_addc_u32 s50, s27, 0
	s_add_u32 s51, s26, 0x34b00000
	s_addc_u32 s52, s27, 0
	s_waitcnt vmcnt(38)
	v_and_b32_e32 v4, 31, v1
	v_readlane_b32 s8, v255, 31
	s_add_u32 s34, s14, 0x8500000
	v_lshlrev_b32_e32 v2, 1, v4
	v_mov_b32_e32 v3, 0
	s_waitcnt vmcnt(5)
	v_ashrrev_i32_e32 v134, 5, v1
	v_readlane_b32 s1, v255, 24
	s_addc_u32 s35, s15, 0
	s_add_i32 s8, 0, 0x24194
	s_mov_b32 s23, 0
	v_cmp_eq_u32_e64 s[72:73], 0, v1
	v_cmp_eq_u32_e64 s[74:75], 0, v4
	v_lshlrev_b32_e32 v120, 3, v4
	v_mov_b32_e32 v121, v3
	v_add_u32_e32 v135, 2, v134
	s_mov_b64 s[0:1], -1
	v_mov_b32_e32 v136, s8
	s_add_i32 s53, 0, 0x241a4
	s_add_i32 s54, 0, 0x241b4
	v_lshlrev_b32_e32 v122, 2, v2
	s_movk_i32 s55, 0x1000
	s_mov_b64 s[36:37], 0x400
	s_add_i32 s64, 0, 0x241a0
	s_movk_i32 s65, 0xc00
	s_mov_b64 s[38:39], 0x1000
	s_mov_b64 s[40:41], -1
	v_readlane_b32 s2, v255, 25
	v_readlane_b32 s3, v255, 26
	v_readlane_b32 s4, v255, 27
	v_readlane_b32 s5, v255, 28
	v_readlane_b32 s6, v255, 29
	v_readlane_b32 s7, v255, 30
	v_readlane_b32 s9, v255, 32
	v_readlane_b32 s10, v255, 33
	v_readlane_b32 s11, v255, 34
	v_readlane_b32 s12, v255, 35
	v_readlane_b32 s13, v255, 36
	s_branch .LBB0_1193
